# adds: attention row-max over 32 logits computed with 16 v_max3 (identical result for non-NaN), instead of 53 canonicalising max ops
# speedup vs baseline: 1.0133x; 1.0056x over previous
; __device__ __forceinline__ void attn_tile(LAS unsigned char* lds, int bo, const bf16x8 (&qr)[4], f32x16& o0, f32x16& o1, float& mrun, float& lrun, int t, int qlo, int r32, int hi) {
;     ...
;     float mx = fmaxf(p0[0], p1[0]);
; #pragma unroll
;     for (int r = 1; r < 16; ++r) mx = fmaxf(mx, fmaxf(p0[r], p1[r]));
;     mx = fmaxf(mx, __shfl_xor(mx, 32));
;     if (__any(mx > mrun)) {
;         const float mnew = fmaxf(mrun, mx);
;         const float alpha = __builtin_amdgcn_exp2f(mrun - mnew);
;         mrun = mnew; lrun *= alpha;
; #pragma unroll
;         for (int r = 0; r < 16; ++r) { o0[r] *= alpha; o1[r] *= alpha; }
;     }
.LBB0_631:
	s_nop 10
	v_max3_f32 v0, v48, v49, v50
	v_max3_f32 v2, v64, v65, v66
	v_max3_f32 v0, v0, v51, v52
	v_max3_f32 v2, v2, v67, v68
	v_max3_f32 v0, v0, v53, v54
	v_max3_f32 v2, v2, v69, v70
	v_max3_f32 v0, v0, v55, v56
	v_max3_f32 v2, v2, v71, v72
	v_max3_f32 v0, v0, v57, v58
	v_max3_f32 v2, v2, v73, v74
	v_max3_f32 v0, v0, v59, v60
	v_max3_f32 v2, v2, v75, v76
	v_max3_f32 v0, v0, v61, v62
	v_max3_f32 v2, v2, v77, v78
	v_max3_f32 v0, v0, v63, v79
	v_max_f32_e32 v0, v0, v2
	ds_bpermute_b32 v2, v140, v0
	s_waitcnt lgkmcnt(0)
	v_max_f32_e32 v2, v2, v2
	v_max_f32_e32 v0, v0, v2
	v_cmp_gt_f32_e32 vcc, v0, v165
	s_cbranch_vccz .LBB0_633
	v_max_f32_e32 v0, v0, v0
	v_max_f32_e32 v2, v165, v165
	v_max_f32_e32 v2, v2, v0
	v_sub_f32_e32 v0, v165, v2
	v_exp_f32_e32 v0, v0
	v_mov_b32_e32 v165, v2
	v_mul_f32_e32 v164, v164, v0
	v_pk_mul_f32 v[46:47], v[46:47], v[0:1] op_sel_hi:[1,0]
	v_pk_mul_f32 v[44:45], v[44:45], v[0:1] op_sel_hi:[1,0]
	v_pk_mul_f32 v[42:43], v[42:43], v[0:1] op_sel_hi:[1,0]
	v_pk_mul_f32 v[40:41], v[40:41], v[0:1] op_sel_hi:[1,0]
	v_pk_mul_f32 v[38:39], v[38:39], v[0:1] op_sel_hi:[1,0]
	v_pk_mul_f32 v[36:37], v[36:37], v[0:1] op_sel_hi:[1,0]
	v_pk_mul_f32 v[34:35], v[34:35], v[0:1] op_sel_hi:[1,0]
	v_pk_mul_f32 v[32:33], v[32:33], v[0:1] op_sel_hi:[1,0]
	v_pk_mul_f32 v[30:31], v[30:31], v[0:1] op_sel_hi:[1,0]
	v_pk_mul_f32 v[28:29], v[28:29], v[0:1] op_sel_hi:[1,0]
	v_pk_mul_f32 v[26:27], v[26:27], v[0:1] op_sel_hi:[1,0]
	v_pk_mul_f32 v[24:25], v[24:25], v[0:1] op_sel_hi:[1,0]
	v_pk_mul_f32 v[22:23], v[22:23], v[0:1] op_sel_hi:[1,0]
	v_pk_mul_f32 v[20:21], v[20:21], v[0:1] op_sel_hi:[1,0]
	v_pk_mul_f32 v[18:19], v[18:19], v[0:1] op_sel_hi:[1,0]
	v_pk_mul_f32 v[16:17], v[16:17], v[0:1] op_sel_hi:[1,0]
